# attention epilogue: O staged through wave-private LDS as bf16 rows, 8 dwordx4 stores per lane instead of 64 short stores
# speedup vs baseline: 1.0198x; 1.0014x over previous
; __device__ __forceinline__ unsigned short f2bf_rne(float f) { unsigned u = __builtin_bit_cast(unsigned, f); return (unsigned short)((u + 0x7fffu + ((u >> 16) & 1u)) >> 16); }
; __device__ __forceinline__ int crow(int r, int hi) { return (r & 3) + 8 * (r >> 2) + 4 * hi; }
; template <typename TQ>
; __device__ __forceinline__ void attn_dense_body(const TQ* __restrict__ Qb, const bf16* __restrict__ Kh, const bf16* __restrict__ Vh,
;                                                 unsigned short* __restrict__ Ob, int seq, char* lds, const int wave_s) {
;     ...
;   if (hi == 0) li_l[r32] = l_reg; asm volatile("s_waitcnt lgkmcnt(0)" ::: "memory");
;   float rli[16];
; #pragma unroll
;   for (int r = 0; r < 16; ++r) rli[r] = __builtin_amdgcn_rcpf(li_l[crow(r, hi)]);
;   unsigned short* Ow = Ob + (long)(wid * QBLK) * LDO;
; #pragma unroll
;   for (int r = 0; r < 16; ++r) { int orow = crow(r, hi);
;     for (int d0 = 0; d0 < 4; ++d0) Ow[(long)orow * LDO + d0 * 32 + r32] = f2bf_rne(o[d0][r] * rli[r]); }
.LBB0_569:
	s_or_b64 exec, exec, s[40:41]
	s_waitcnt lgkmcnt(0)
	v_add_u32_e32 v88, s1, v180
	ds_read_b128 v[64:67], v88
	ds_read_b128 v[68:71], v88 offset:32
	ds_read_b128 v[92:95], v88 offset:64
	ds_read_b128 v[96:99], v88 offset:96
	s_lshl_b64 s[38:39], s[2:3], 11
	s_add_u32 s2, s4, s38
	s_addc_u32 s38, s5, s39
	s_add_u32 s2, s2, s42
	s_addc_u32 s39, s38, s43
	s_add_u32 s38, s2, s14
	s_addc_u32 s39, s39, s15
	s_sub_u32 s40, s1, 0x20000
	s_lshl_b32 s40, s40, 5
	s_add_u32 s40, s40, 0x10000
	v_lshlrev_b32_e32 v100, 10, v179
	v_lshl_add_u32 v100, v178, 1, v100
	v_add_u32_e32 v100, s40, v100
	v_lshl_add_u32 v101, v179, 5, v178
	v_lshrrev_b32_e32 v102, 4, v101
	v_and_b32_e32 v103, 15, v101
	v_lshlrev_b32_e32 v104, 8, v102
	v_lshl_add_u32 v104, v103, 4, v104
	v_add_u32_e32 v104, s40, v104
	v_lshlrev_b32_e32 v105, 11, v102
	v_lshl_add_u32 v105, v103, 4, v105
	s_waitcnt lgkmcnt(0)
	v_rcp_f32_e32 v72, v64
	v_rcp_f32_e32 v73, v65
	v_rcp_f32_e32 v74, v66
	v_rcp_f32_e32 v75, v67
	v_rcp_f32_e32 v76, v68
	v_rcp_f32_e32 v77, v69
	v_rcp_f32_e32 v78, v70
	v_rcp_f32_e32 v79, v71
	v_rcp_f32_e32 v80, v92
	v_rcp_f32_e32 v81, v93
	v_rcp_f32_e32 v82, v94
	v_rcp_f32_e32 v83, v95
	v_rcp_f32_e32 v84, v96
	v_rcp_f32_e32 v85, v97
	v_rcp_f32_e32 v86, v98
	v_rcp_f32_e32 v87, v99
	s_nop 0
	v_pk_mul_f32 v[106:107], v[0:1], v[72:73]
	v_cvt_pk_bf16_f32 v106, v106, v107
	ds_write_b16 v100, v106 offset:0
	ds_write_b16_d16_hi v100, v106 offset:256
	v_pk_mul_f32 v[108:109], v[2:3], v[74:75]
	v_cvt_pk_bf16_f32 v108, v108, v109
	ds_write_b16 v100, v108 offset:512
	ds_write_b16_d16_hi v100, v108 offset:768
	v_pk_mul_f32 v[110:111], v[4:5], v[76:77]
	v_cvt_pk_bf16_f32 v110, v110, v111
	ds_write_b16 v100, v110 offset:2048
	ds_write_b16_d16_hi v100, v110 offset:2304
	v_pk_mul_f32 v[112:113], v[6:7], v[78:79]
	v_cvt_pk_bf16_f32 v112, v112, v113
	ds_write_b16 v100, v112 offset:2560
	ds_write_b16_d16_hi v100, v112 offset:2816
	v_pk_mul_f32 v[106:107], v[8:9], v[80:81]
	v_cvt_pk_bf16_f32 v106, v106, v107
	ds_write_b16 v100, v106 offset:4096
	ds_write_b16_d16_hi v100, v106 offset:4352
	v_pk_mul_f32 v[108:109], v[10:11], v[82:83]
	v_cvt_pk_bf16_f32 v108, v108, v109
	ds_write_b16 v100, v108 offset:4608
	ds_write_b16_d16_hi v100, v108 offset:4864
	v_pk_mul_f32 v[110:111], v[12:13], v[84:85]
	v_cvt_pk_bf16_f32 v110, v110, v111
	ds_write_b16 v100, v110 offset:6144
	ds_write_b16_d16_hi v100, v110 offset:6400
	v_pk_mul_f32 v[112:113], v[14:15], v[86:87]
	v_cvt_pk_bf16_f32 v112, v112, v113
	ds_write_b16 v100, v112 offset:6656
	ds_write_b16_d16_hi v100, v112 offset:6912
	v_pk_mul_f32 v[106:107], v[48:49], v[72:73]
	v_cvt_pk_bf16_f32 v106, v106, v107
	ds_write_b16 v100, v106 offset:64
	ds_write_b16_d16_hi v100, v106 offset:320
	v_pk_mul_f32 v[108:109], v[50:51], v[74:75]
	v_cvt_pk_bf16_f32 v108, v108, v109
	ds_write_b16 v100, v108 offset:576
	ds_write_b16_d16_hi v100, v108 offset:832
	v_pk_mul_f32 v[110:111], v[52:53], v[76:77]
	v_cvt_pk_bf16_f32 v110, v110, v111
	ds_write_b16 v100, v110 offset:2112
	ds_write_b16_d16_hi v100, v110 offset:2368
	v_pk_mul_f32 v[112:113], v[54:55], v[78:79]
	v_cvt_pk_bf16_f32 v112, v112, v113
	ds_write_b16 v100, v112 offset:2624
	ds_write_b16_d16_hi v100, v112 offset:2880
	v_pk_mul_f32 v[106:107], v[56:57], v[80:81]
	v_cvt_pk_bf16_f32 v106, v106, v107
	ds_write_b16 v100, v106 offset:4160
	ds_write_b16_d16_hi v100, v106 offset:4416
	v_pk_mul_f32 v[108:109], v[58:59], v[82:83]
	v_cvt_pk_bf16_f32 v108, v108, v109
	ds_write_b16 v100, v108 offset:4672
	ds_write_b16_d16_hi v100, v108 offset:4928
	v_pk_mul_f32 v[110:111], v[60:61], v[84:85]
	v_cvt_pk_bf16_f32 v110, v110, v111
	ds_write_b16 v100, v110 offset:6208
	ds_write_b16_d16_hi v100, v110 offset:6464
	v_pk_mul_f32 v[112:113], v[62:63], v[86:87]
	v_cvt_pk_bf16_f32 v112, v112, v113
	ds_write_b16 v100, v112 offset:6720
	ds_write_b16_d16_hi v100, v112 offset:6976
	v_pk_mul_f32 v[106:107], v[32:33], v[72:73]
	v_cvt_pk_bf16_f32 v106, v106, v107
	ds_write_b16 v100, v106 offset:128
	ds_write_b16_d16_hi v100, v106 offset:384
	v_pk_mul_f32 v[108:109], v[34:35], v[74:75]
	v_cvt_pk_bf16_f32 v108, v108, v109
	ds_write_b16 v100, v108 offset:640
	ds_write_b16_d16_hi v100, v108 offset:896
	v_pk_mul_f32 v[110:111], v[36:37], v[76:77]
	v_cvt_pk_bf16_f32 v110, v110, v111
	ds_write_b16 v100, v110 offset:2176
	ds_write_b16_d16_hi v100, v110 offset:2432
	v_pk_mul_f32 v[112:113], v[38:39], v[78:79]
	v_cvt_pk_bf16_f32 v112, v112, v113
	ds_write_b16 v100, v112 offset:2688
	ds_write_b16_d16_hi v100, v112 offset:2944
	v_pk_mul_f32 v[106:107], v[40:41], v[80:81]
	v_cvt_pk_bf16_f32 v106, v106, v107
	ds_write_b16 v100, v106 offset:4224
	ds_write_b16_d16_hi v100, v106 offset:4480
	v_pk_mul_f32 v[108:109], v[42:43], v[82:83]
	v_cvt_pk_bf16_f32 v108, v108, v109
	ds_write_b16 v100, v108 offset:4736
	ds_write_b16_d16_hi v100, v108 offset:4992
	v_pk_mul_f32 v[110:111], v[44:45], v[84:85]
	v_cvt_pk_bf16_f32 v110, v110, v111
	ds_write_b16 v100, v110 offset:6272
	ds_write_b16_d16_hi v100, v110 offset:6528
	v_pk_mul_f32 v[112:113], v[46:47], v[86:87]
	v_cvt_pk_bf16_f32 v112, v112, v113
	ds_write_b16 v100, v112 offset:6784
	ds_write_b16_d16_hi v100, v112 offset:7040
	v_pk_mul_f32 v[106:107], v[16:17], v[72:73]
	v_cvt_pk_bf16_f32 v106, v106, v107
	ds_write_b16 v100, v106 offset:192
	ds_write_b16_d16_hi v100, v106 offset:448
	v_pk_mul_f32 v[108:109], v[18:19], v[74:75]
	v_cvt_pk_bf16_f32 v108, v108, v109
	ds_write_b16 v100, v108 offset:704
	ds_write_b16_d16_hi v100, v108 offset:960
	v_pk_mul_f32 v[110:111], v[20:21], v[76:77]
	v_cvt_pk_bf16_f32 v110, v110, v111
	ds_write_b16 v100, v110 offset:2240
	ds_write_b16_d16_hi v100, v110 offset:2496
	v_pk_mul_f32 v[112:113], v[22:23], v[78:79]
	v_cvt_pk_bf16_f32 v112, v112, v113
	ds_write_b16 v100, v112 offset:2752
	ds_write_b16_d16_hi v100, v112 offset:3008
	v_pk_mul_f32 v[106:107], v[24:25], v[80:81]
	v_cvt_pk_bf16_f32 v106, v106, v107
	ds_write_b16 v100, v106 offset:4288
	ds_write_b16_d16_hi v100, v106 offset:4544
	v_pk_mul_f32 v[108:109], v[26:27], v[82:83]
	v_cvt_pk_bf16_f32 v108, v108, v109
	ds_write_b16 v100, v108 offset:4800
	ds_write_b16_d16_hi v100, v108 offset:5056
	v_pk_mul_f32 v[110:111], v[28:29], v[84:85]
	v_cvt_pk_bf16_f32 v110, v110, v111
	ds_write_b16 v100, v110 offset:6336
	ds_write_b16_d16_hi v100, v110 offset:6592
	v_pk_mul_f32 v[112:113], v[30:31], v[86:87]
	v_cvt_pk_bf16_f32 v112, v112, v113
	ds_write_b16 v100, v112 offset:6848
	ds_write_b16_d16_hi v100, v112 offset:7104
	s_waitcnt lgkmcnt(0)
; __device__ __forceinline__ unsigned short f2bf_rne(float f) { unsigned u = __builtin_bit_cast(unsigned, f); return (unsigned short)((u + 0x7fffu + ((u >> 16) & 1u)) >> 16); }
; __device__ __forceinline__ int crow(int r, int hi) { return (r & 3) + 8 * (r >> 2) + 4 * hi; }
; template <typename TQ>
; __device__ __forceinline__ void attn_dense_body(const TQ* __restrict__ Qb, const bf16* __restrict__ Kh, const bf16* __restrict__ Vh,
;                                                 unsigned short* __restrict__ Ob, int seq, char* lds, const int wave_s) {
;     ...
;   unsigned short* Ow = Ob + (long)(wid * QBLK) * LDO;
; #pragma unroll
;   for (int r = 0; r < 16; ++r) { int orow = crow(r, hi);
;     for (int d0 = 0; d0 < 4; ++d0) Ow[(long)orow * LDO + d0 * 32 + r32] = f2bf_rne(o[d0][r] * rli[r]); }
	ds_read_b128 v[112:115], v104 offset:0
	ds_read_b128 v[116:119], v104 offset:1024
	ds_read_b128 v[120:123], v104 offset:2048
	ds_read_b128 v[124:127], v104 offset:3072
	ds_read_b128 v[128:131], v104 offset:4096
	ds_read_b128 v[132:135], v104 offset:5120
	ds_read_b128 v[136:139], v104 offset:6144
	ds_read_b128 v[140:143], v104 offset:7168
	s_waitcnt lgkmcnt(7)
	global_store_dwordx4 v105, v[112:115], s[38:39]
	s_add_u32 s38, s38, 0x2000
	s_addc_u32 s39, s39, 0
	s_waitcnt lgkmcnt(6)
	global_store_dwordx4 v105, v[116:119], s[38:39]
	s_add_u32 s38, s38, 0x2000
	s_addc_u32 s39, s39, 0
	s_waitcnt lgkmcnt(5)
	global_store_dwordx4 v105, v[120:123], s[38:39]
	s_add_u32 s38, s38, 0x2000
	s_addc_u32 s39, s39, 0
	s_waitcnt lgkmcnt(4)
	global_store_dwordx4 v105, v[124:127], s[38:39]
	s_add_u32 s38, s38, 0x2000
	s_addc_u32 s39, s39, 0
	s_waitcnt lgkmcnt(3)
	global_store_dwordx4 v105, v[128:131], s[38:39]
	s_add_u32 s38, s38, 0x2000
	s_addc_u32 s39, s39, 0
	s_waitcnt lgkmcnt(2)
	global_store_dwordx4 v105, v[132:135], s[38:39]
	s_add_u32 s38, s38, 0x2000
	s_addc_u32 s39, s39, 0
	s_waitcnt lgkmcnt(1)
	global_store_dwordx4 v105, v[136:139], s[38:39]
	s_add_u32 s38, s38, 0x2000
	s_addc_u32 s39, s39, 0
	s_waitcnt lgkmcnt(0)
	global_store_dwordx4 v105, v[140:143], s[38:39]
	s_add_i32 s48, s48, s96
	s_cmpk_gt_i32 s48, 0x9ff
	s_waitcnt lgkmcnt(0)
	s_barrier
	s_cbranch_scc1 .LBB0_565
